# mLSTM gate prefix: gates and the running max reach the prefix block through registers (v_readlane carry) instead of two LDS round trips
# speedup vs baseline: 1.0172x; 1.0046x over previous
.LBB0_1137:
	s_or_b64 exec, exec, s[44:45]
	s_add_u32 s22, s36, s94
	s_addc_u32 s23, s37, 0
	s_add_u32 s72, s30, s8
	s_addc_u32 s73, s31, 0
	s_lshl_b32 s4, s84, 2
	s_add_u32 s8, s34, s4
	v_mov_b32_e32 v65, v140
	s_addc_u32 s9, s35, 0
	v_mov_b32_e32 v67, v140
	v_lshl_add_u64 v[150:151], s[22:23], 0, v[64:65]
	v_lshl_add_u64 v[64:65], s[8:9], 0, v[66:67]
	v_lshlrev_b32_e32 v188, 2, v145
	v_lshlrev_b32_e32 v191, 4, v69
	s_mov_b32 s85, 0
	v_cmp_eq_u32_e64 s[44:45], 0, v146
	v_cmp_gt_i32_e64 s[46:47], 16, v141
	v_cmp_lt_i32_e64 s[48:49], 0, v141
	v_cmp_lt_i32_e64 s[50:51], 1, v141
	v_cmp_lt_i32_e64 s[52:53], 3, v141
	v_cmp_eq_u32_e64 s[54:55], 7, v141
	v_lshl_add_u64 v[152:153], v[64:65], 0, s[94:95]
	v_lshlrev_b32_e32 v194, 4, v146
	v_lshlrev_b32_e32 v190, 2, v68
	v_mov_b32_e32 v88, 0
	s_xor_b64 s[56:57], s[56:57], -1
	s_mov_b32 s88, 0
	v_mov_b32_e32 v89, 0
	v_mov_b32_e32 v90, 0
	v_mov_b32_e32 v100, 0
	v_mov_b32_e32 v91, 0
	v_mov_b32_e32 v101, 0
	v_mov_b32_e32 v102, 0
	v_mov_b32_e32 v104, 0
	v_mov_b32_e32 v103, 0
	v_mov_b32_e32 v105, 0
	v_mov_b32_e32 v106, 0
	v_mov_b32_e32 v109, 0
	v_mov_b32_e32 v107, 0
	v_mov_b32_e32 v110, 0
	v_mov_b32_e32 v108, 0
	v_mov_b32_e32 v111, 0
	v_mov_b32_e32 v216, 0
	s_branch .LBB0_1139

.LBB0_1143:
	s_or_b64 exec, exec, s[8:9]
	s_and_saveexec_b64 s[8:9], s[46:47]
	s_cbranch_execz .LBB0_1154
	v_mov_b32_e32 v214, v66
	v_mov_b32_e32 v215, v64
	v_mov_b32_e32 v65, 0
	v_mov_b32_e32 v64, 0xf149f2ca
	s_and_saveexec_b64 s[64:65], s[42:43]
	v_mov_b32_e32 v64, v214
	v_mov_b32_e32 v65, v215
	s_or_b64 exec, exec, s[64:65]
	s_waitcnt lgkmcnt(0)
	v_add_f32_dpp v66, v64, v65 row_shr:1 row_mask:0xf bank_mask:0xf bound_ctrl:1
	v_max_f32_e32 v67, v64, v64
	v_max_f32_e32 v66, v66, v67
	v_cndmask_b32_e64 v66, v64, v66, s[48:49]
	v_add_f32_dpp v67, v65, v65 row_shr:1 row_mask:0xf bank_mask:0xf bound_ctrl:1
	v_cndmask_b32_e64 v67, v65, v67, s[48:49]
	v_max_f32_e32 v69, v66, v66
	s_nop 0
	v_add_f32_dpp v68, v66, v67 row_shr:2 row_mask:0xf bank_mask:0xf bound_ctrl:1
	v_max_f32_e32 v68, v68, v69
	v_add_f32_dpp v69, v67, v67 row_shr:2 row_mask:0xf bank_mask:0xf bound_ctrl:1
	v_cndmask_b32_e64 v66, v66, v68, s[50:51]
	v_cndmask_b32_e64 v67, v67, v69, s[50:51]
	v_max_f32_e32 v69, v66, v66
	s_nop 0
	v_add_f32_dpp v68, v66, v67 row_shr:4 row_mask:0xf bank_mask:0xf bound_ctrl:1
	v_max_f32_e32 v68, v68, v69
	v_cndmask_b32_e64 v66, v66, v68, s[52:53]
	v_mov_b32_e32 v68, v216
	v_add_f32_dpp v69, v67, v67 row_shr:4 row_mask:0xf bank_mask:0xf bound_ctrl:1
	v_cndmask_b32_e64 v67, v67, v69, s[52:53]
	v_max_f32_e32 v66, v66, v66
	s_waitcnt lgkmcnt(0)
	v_add_f32_e32 v67, v68, v67
	v_max_f32_e32 v66, v67, v66
	v_mov_b32_e32 v67, 0
	v_sub_f32_e32 v64, v64, v66
	v_mul_f32_e32 v64, 0x3fb8aa3b, v64
	v_mov_b32_dpp v67, v66 row_shr:1 row_mask:0xf bank_mask:0xf
	v_cndmask_b32_e64 v67, v67, v68, s[38:39]
	v_add_f32_e32 v65, v65, v67
	v_sub_f32_e32 v65, v65, v66
	v_mul_f32_e32 v65, 0x3fb8aa3b, v65
	v_exp_f32_e32 v65, v65
	v_exp_f32_e32 v64, v64
	v_add_u32_e32 v67, 0x8800, v145
	ds_write2_b32 v67, v65, v64 offset0:64 offset1:80
	ds_write_b32 v145, v66 offset:35200
	v_readlane_b32 s64, v66, 7
	s_nop 3
	v_mov_b32_e32 v216, s64
	s_and_b64 exec, exec, s[54:55]
	ds_write_b32 v140, v66 offset:35328

.LBB0_1176:
	s_or_b64 exec, exec, s[8:9]
	s_and_saveexec_b64 s[8:9], s[46:47]
	s_cbranch_execz .LBB0_1187
	v_mov_b32_e32 v214, v66
	v_mov_b32_e32 v215, v64
	v_mov_b32_e32 v65, 0
	v_mov_b32_e32 v64, 0xf149f2ca
	s_and_saveexec_b64 s[64:65], s[42:43]
	v_mov_b32_e32 v64, v214
	v_mov_b32_e32 v65, v215
	s_or_b64 exec, exec, s[64:65]
	s_waitcnt lgkmcnt(0)
	v_add_f32_dpp v66, v64, v65 row_shr:1 row_mask:0xf bank_mask:0xf bound_ctrl:1
	v_max_f32_e32 v67, v64, v64
	v_max_f32_e32 v66, v66, v67
	v_cndmask_b32_e64 v66, v64, v66, s[48:49]
	v_add_f32_dpp v67, v65, v65 row_shr:1 row_mask:0xf bank_mask:0xf bound_ctrl:1
	v_cndmask_b32_e64 v67, v65, v67, s[48:49]
	v_max_f32_e32 v69, v66, v66
	s_nop 0
	v_add_f32_dpp v68, v66, v67 row_shr:2 row_mask:0xf bank_mask:0xf bound_ctrl:1
	v_max_f32_e32 v68, v68, v69
	v_add_f32_dpp v69, v67, v67 row_shr:2 row_mask:0xf bank_mask:0xf bound_ctrl:1
	v_cndmask_b32_e64 v66, v66, v68, s[50:51]
	v_cndmask_b32_e64 v67, v67, v69, s[50:51]
	v_max_f32_e32 v69, v66, v66
	s_nop 0
	v_add_f32_dpp v68, v66, v67 row_shr:4 row_mask:0xf bank_mask:0xf bound_ctrl:1
	v_max_f32_e32 v68, v68, v69
	v_cndmask_b32_e64 v66, v66, v68, s[52:53]
	v_mov_b32_e32 v68, v216
	v_add_f32_dpp v69, v67, v67 row_shr:4 row_mask:0xf bank_mask:0xf bound_ctrl:1
	v_cndmask_b32_e64 v67, v67, v69, s[52:53]
	v_max_f32_e32 v66, v66, v66
	s_waitcnt lgkmcnt(0)
	v_add_f32_e32 v67, v68, v67
	v_max_f32_e32 v66, v67, v66
	v_mov_b32_e32 v67, 0
	v_sub_f32_e32 v64, v64, v66
	v_mul_f32_e32 v64, 0x3fb8aa3b, v64
	v_mov_b32_dpp v67, v66 row_shr:1 row_mask:0xf bank_mask:0xf
	v_cndmask_b32_e64 v67, v67, v68, s[38:39]
	v_add_f32_e32 v65, v65, v67
	v_sub_f32_e32 v65, v65, v66
	v_mul_f32_e32 v65, 0x3fb8aa3b, v65
	v_exp_f32_e32 v65, v65
	v_exp_f32_e32 v64, v64
	v_add_u32_e32 v67, 0x8800, v145
	ds_write2_b32 v67, v65, v64 offset0:160 offset1:176
	ds_write_b32 v145, v66 offset:35264
	v_readlane_b32 s64, v66, 7
	s_nop 3
	v_mov_b32_e32 v216, s64
	s_and_b64 exec, exec, s[54:55]
	ds_write_b32 v140, v66 offset:35328

.LBB0_1242:
	s_or_b64 exec, exec, s[8:9]
	s_and_saveexec_b64 s[8:9], s[46:47]
	s_cbranch_execz .LBB0_1253
	v_mov_b32_e32 v214, v66
	v_mov_b32_e32 v215, v64
	v_mov_b32_e32 v64, 0xf149f2ca
	v_mov_b32_e32 v65, 0
	s_and_saveexec_b64 s[64:65], s[42:43]
	v_mov_b32_e32 v64, v214
	v_mov_b32_e32 v65, v215
	s_or_b64 exec, exec, s[64:65]
	s_waitcnt lgkmcnt(0)
	v_add_f32_dpp v66, v64, v65 row_shr:1 row_mask:0xf bank_mask:0xf bound_ctrl:1
	v_max_f32_e32 v67, v64, v64
	v_max_f32_e32 v66, v66, v67
	v_cndmask_b32_e64 v66, v64, v66, s[48:49]
	v_add_f32_dpp v67, v65, v65 row_shr:1 row_mask:0xf bank_mask:0xf bound_ctrl:1
	v_cndmask_b32_e64 v67, v65, v67, s[48:49]
	v_max_f32_e32 v69, v66, v66
	s_nop 0
	v_add_f32_dpp v68, v66, v67 row_shr:2 row_mask:0xf bank_mask:0xf bound_ctrl:1
	v_max_f32_e32 v68, v68, v69
	v_add_f32_dpp v69, v67, v67 row_shr:2 row_mask:0xf bank_mask:0xf bound_ctrl:1
	v_cndmask_b32_e64 v67, v67, v69, s[50:51]
	v_cndmask_b32_e64 v66, v66, v68, s[50:51]
	v_max_f32_e32 v69, v66, v66
	s_nop 0
	v_add_f32_dpp v68, v66, v67 row_shr:4 row_mask:0xf bank_mask:0xf bound_ctrl:1
	v_max_f32_e32 v68, v68, v69
	v_cndmask_b32_e64 v66, v66, v68, s[52:53]
	v_mov_b32_e32 v68, v216
	v_add_f32_dpp v69, v67, v67 row_shr:4 row_mask:0xf bank_mask:0xf bound_ctrl:1
	v_cndmask_b32_e64 v67, v67, v69, s[52:53]
	v_max_f32_e32 v66, v66, v66
	s_waitcnt lgkmcnt(0)
	v_add_f32_e32 v67, v68, v67
	v_max_f32_e32 v66, v67, v66
	v_mov_b32_e32 v67, 0
	v_sub_f32_e32 v64, v64, v66
	v_mul_f32_e32 v64, 0x3fb8aa3b, v64
	v_mov_b32_dpp v67, v66 row_shr:1 row_mask:0xf bank_mask:0xf
	v_cndmask_b32_e64 v67, v67, v68, s[38:39]
	v_add_f32_e32 v65, v65, v67
	v_sub_f32_e32 v65, v65, v66
	v_mul_f32_e32 v65, 0x3fb8aa3b, v65
	v_exp_f32_e32 v65, v65
	v_exp_f32_e32 v64, v64
	v_add_u32_e32 v67, 0x8800, v145
	ds_write2_b32 v67, v65, v64 offset0:160 offset1:176
	ds_write_b32 v145, v66 offset:35264
	v_readlane_b32 s64, v66, 7
	s_nop 3
	v_mov_b32_e32 v216, s64
	s_and_b64 exec, exec, s[54:55]
	ds_write_b32 v140, v66 offset:35328

.LBB0_1437:
	s_or_b64 exec, exec, s[8:9]
	s_add_u32 s8, s36, s94
	v_and_b32_e32 v68, 15, v141
	s_addc_u32 s9, s37, 0
	s_movk_i32 s4, 0x80
	v_cmp_eq_u32_e64 s[44:45], 0, v68
	v_ashrrev_i32_e32 v69, 4, v141
	v_mov_b32_e32 v67, v140
	s_add_u32 s58, s30, s84
	v_cmp_gt_i32_e64 s[42:43], s4, v141
	s_mov_b32 s73, 0
	v_mov_b32_e32 v64, 0
	v_cndmask_b32_e64 v184, 0, 1.0, s[44:45]
	v_lshlrev_b32_e32 v185, 2, v144
	v_lshlrev_b32_e32 v186, 4, v65
	v_lshl_add_u64 v[150:151], s[8:9], 0, v[66:67]
	s_addc_u32 s59, s31, 0
	v_cmp_gt_i32_e64 s[46:47], 16, v141
	v_cmp_lt_i32_e64 s[48:49], 0, v141
	v_cmp_lt_i32_e64 s[50:51], 1, v141
	v_cmp_lt_i32_e64 s[52:53], 3, v141
	v_cmp_eq_u32_e64 s[54:55], 7, v141
	v_lshlrev_b32_e32 v183, 6, v141
	v_lshlrev_b32_e32 v188, 4, v68
	v_lshlrev_b32_e32 v189, 2, v69
	s_xor_b64 s[56:57], s[56:57], -1
	s_mov_b32 s85, 0
	v_mov_b32_e32 v65, 0
	v_mov_b32_e32 v66, 0
	v_mov_b32_e32 v67, 0
	v_mov_b32_e32 v76, 0
	v_mov_b32_e32 v77, 0
	v_mov_b32_e32 v78, 0
	v_mov_b32_e32 v79, 0
	v_mov_b32_e32 v72, 0
	v_mov_b32_e32 v73, 0
	v_mov_b32_e32 v74, 0
	v_mov_b32_e32 v75, 0
	v_mov_b32_e32 v68, 0
	v_mov_b32_e32 v69, 0
	v_mov_b32_e32 v70, 0
	v_mov_b32_e32 v71, 0
	v_mov_b32_e32 v194, 0
	s_branch .LBB0_1439

.LBB0_1443:
	s_or_b64 exec, exec, s[8:9]
	s_and_saveexec_b64 s[8:9], s[46:47]
	s_cbranch_execz .LBB0_1452
	v_mov_b32_e32 v192, v82
	v_mov_b32_e32 v193, v80
	v_mov_b32_e32 v81, 0
	v_mov_b32_e32 v80, 0xf149f2ca
	s_and_saveexec_b64 s[64:65], s[40:41]
	v_mov_b32_e32 v80, v192
	v_mov_b32_e32 v81, v193
	s_or_b64 exec, exec, s[64:65]
	s_waitcnt lgkmcnt(0)
	v_add_f32_dpp v82, v80, v81 row_shr:1 row_mask:0xf bank_mask:0xf bound_ctrl:1
	v_max_f32_e32 v83, v80, v80
	v_max_f32_e32 v82, v82, v83
	v_cndmask_b32_e64 v82, v80, v82, s[48:49]
	v_add_f32_dpp v83, v81, v81 row_shr:1 row_mask:0xf bank_mask:0xf bound_ctrl:1
	v_cndmask_b32_e64 v83, v81, v83, s[48:49]
	v_max_f32_e32 v85, v82, v82
	s_nop 0
	v_add_f32_dpp v84, v82, v83 row_shr:2 row_mask:0xf bank_mask:0xf bound_ctrl:1
	v_max_f32_e32 v84, v84, v85
	v_add_f32_dpp v85, v83, v83 row_shr:2 row_mask:0xf bank_mask:0xf bound_ctrl:1
	v_cndmask_b32_e64 v82, v82, v84, s[50:51]
	v_cndmask_b32_e64 v83, v83, v85, s[50:51]
	v_max_f32_e32 v85, v82, v82
	s_nop 0
	v_add_f32_dpp v84, v82, v83 row_shr:4 row_mask:0xf bank_mask:0xf bound_ctrl:1
	v_max_f32_e32 v84, v84, v85
	v_cndmask_b32_e64 v82, v82, v84, s[52:53]
	v_mov_b32_e32 v84, v194
	v_add_f32_dpp v85, v83, v83 row_shr:4 row_mask:0xf bank_mask:0xf bound_ctrl:1
	v_cndmask_b32_e64 v83, v83, v85, s[52:53]
	v_max_f32_e32 v82, v82, v82
	s_waitcnt lgkmcnt(0)
	v_add_f32_e32 v83, v84, v83
	v_max_f32_e32 v82, v83, v82
	v_mov_b32_e32 v83, 0
	v_sub_f32_e32 v80, v80, v82
	v_mul_f32_e32 v80, 0x3fb8aa3b, v80
	v_mov_b32_dpp v83, v82 row_shr:1 row_mask:0xf bank_mask:0xf
	v_cndmask_b32_e64 v83, v83, v84, s[38:39]
	v_add_f32_e32 v81, v81, v83
	v_sub_f32_e32 v81, v81, v82
	v_mul_f32_e32 v81, 0x3fb8aa3b, v81
	v_exp_f32_e32 v81, v81
	v_exp_f32_e32 v80, v80
	v_add_u32_e32 v83, 0x8800, v144
	ds_write2_b32 v83, v81, v80 offset0:64 offset1:80
	ds_write_b32 v144, v82 offset:35200
	v_readlane_b32 s64, v82, 7
	s_nop 3
	v_mov_b32_e32 v194, s64
	s_and_b64 exec, exec, s[54:55]
	ds_write_b32 v140, v82 offset:35328

.LBB0_1474:
	s_or_b64 exec, exec, s[8:9]
	s_and_saveexec_b64 s[8:9], s[46:47]
	s_cbranch_execz .LBB0_1483
	v_mov_b32_e32 v192, v66
	v_mov_b32_e32 v193, v64
	v_mov_b32_e32 v65, 0
	v_mov_b32_e32 v64, 0xf149f2ca
	s_and_saveexec_b64 s[64:65], s[40:41]
	v_mov_b32_e32 v64, v192
	v_mov_b32_e32 v65, v193
	s_or_b64 exec, exec, s[64:65]
	s_waitcnt lgkmcnt(0)
	v_add_f32_dpp v66, v64, v65 row_shr:1 row_mask:0xf bank_mask:0xf bound_ctrl:1
	v_max_f32_e32 v67, v64, v64
	v_max_f32_e32 v66, v66, v67
	v_cndmask_b32_e64 v66, v64, v66, s[48:49]
	v_add_f32_dpp v67, v65, v65 row_shr:1 row_mask:0xf bank_mask:0xf bound_ctrl:1
	v_cndmask_b32_e64 v67, v65, v67, s[48:49]
	v_max_f32_e32 v69, v66, v66
	s_nop 0
	v_add_f32_dpp v68, v66, v67 row_shr:2 row_mask:0xf bank_mask:0xf bound_ctrl:1
	v_max_f32_e32 v68, v68, v69
	v_add_f32_dpp v69, v67, v67 row_shr:2 row_mask:0xf bank_mask:0xf bound_ctrl:1
	v_cndmask_b32_e64 v66, v66, v68, s[50:51]
	v_cndmask_b32_e64 v67, v67, v69, s[50:51]
	v_max_f32_e32 v69, v66, v66
	s_nop 0
	v_add_f32_dpp v68, v66, v67 row_shr:4 row_mask:0xf bank_mask:0xf bound_ctrl:1
	v_max_f32_e32 v68, v68, v69
	v_cndmask_b32_e64 v66, v66, v68, s[52:53]
	v_mov_b32_e32 v68, v194
	v_add_f32_dpp v69, v67, v67 row_shr:4 row_mask:0xf bank_mask:0xf bound_ctrl:1
	v_cndmask_b32_e64 v67, v67, v69, s[52:53]
	v_max_f32_e32 v66, v66, v66
	s_waitcnt lgkmcnt(0)
	v_add_f32_e32 v67, v68, v67
	v_max_f32_e32 v66, v67, v66
	v_mov_b32_e32 v67, 0
	v_sub_f32_e32 v64, v64, v66
	v_mul_f32_e32 v64, 0x3fb8aa3b, v64
	v_mov_b32_dpp v67, v66 row_shr:1 row_mask:0xf bank_mask:0xf
	v_cndmask_b32_e64 v67, v67, v68, s[38:39]
	v_add_f32_e32 v65, v65, v67
	v_sub_f32_e32 v65, v65, v66
	v_mul_f32_e32 v65, 0x3fb8aa3b, v65
	v_exp_f32_e32 v65, v65
	v_exp_f32_e32 v64, v64
	v_add_u32_e32 v67, 0x8800, v144
	ds_write2_b32 v67, v65, v64 offset0:160 offset1:176
	ds_write_b32 v144, v66 offset:35264
	v_readlane_b32 s64, v66, 7
	s_nop 3
	v_mov_b32_e32 v194, s64
	s_and_b64 exec, exec, s[54:55]
	ds_write_b32 v140, v66 offset:35328

.LBB0_1505:
	s_or_b64 exec, exec, s[8:9]
	s_and_saveexec_b64 s[8:9], s[46:47]
	s_cbranch_execz .LBB0_1514
	v_mov_b32_e32 v192, v66
	v_mov_b32_e32 v193, v64
	v_mov_b32_e32 v65, 0
	v_mov_b32_e32 v64, 0xf149f2ca
	s_and_saveexec_b64 s[64:65], s[40:41]
	v_mov_b32_e32 v64, v192
	v_mov_b32_e32 v65, v193
	s_or_b64 exec, exec, s[64:65]
	s_waitcnt lgkmcnt(0)
	v_add_f32_dpp v66, v64, v65 row_shr:1 row_mask:0xf bank_mask:0xf bound_ctrl:1
	v_max_f32_e32 v67, v64, v64
	v_max_f32_e32 v66, v66, v67
	v_cndmask_b32_e64 v66, v64, v66, s[48:49]
	v_add_f32_dpp v67, v65, v65 row_shr:1 row_mask:0xf bank_mask:0xf bound_ctrl:1
	v_cndmask_b32_e64 v67, v65, v67, s[48:49]
	v_max_f32_e32 v69, v66, v66
	s_nop 0
	v_add_f32_dpp v68, v66, v67 row_shr:2 row_mask:0xf bank_mask:0xf bound_ctrl:1
	v_max_f32_e32 v68, v68, v69
	v_add_f32_dpp v69, v67, v67 row_shr:2 row_mask:0xf bank_mask:0xf bound_ctrl:1
	v_cndmask_b32_e64 v66, v66, v68, s[50:51]
	v_cndmask_b32_e64 v67, v67, v69, s[50:51]
	v_max_f32_e32 v69, v66, v66
	s_nop 0
	v_add_f32_dpp v68, v66, v67 row_shr:4 row_mask:0xf bank_mask:0xf bound_ctrl:1
	v_max_f32_e32 v68, v68, v69
	v_cndmask_b32_e64 v66, v66, v68, s[52:53]
	v_mov_b32_e32 v68, v194
	v_add_f32_dpp v69, v67, v67 row_shr:4 row_mask:0xf bank_mask:0xf bound_ctrl:1
	v_cndmask_b32_e64 v67, v67, v69, s[52:53]
	v_max_f32_e32 v66, v66, v66
	s_waitcnt lgkmcnt(0)
	v_add_f32_e32 v67, v68, v67
	v_max_f32_e32 v66, v67, v66
	v_mov_b32_e32 v67, 0
	v_sub_f32_e32 v64, v64, v66
	v_mul_f32_e32 v64, 0x3fb8aa3b, v64
	v_mov_b32_dpp v67, v66 row_shr:1 row_mask:0xf bank_mask:0xf
	v_cndmask_b32_e64 v67, v67, v68, s[38:39]
	v_add_f32_e32 v65, v65, v67
	v_sub_f32_e32 v65, v65, v66
	v_mul_f32_e32 v65, 0x3fb8aa3b, v65
	v_exp_f32_e32 v65, v65
	v_exp_f32_e32 v64, v64
	v_add_u32_e32 v67, 0x8800, v144
	ds_write2_b32 v67, v65, v64 offset0:64 offset1:80
	ds_write_b32 v144, v66 offset:35200
	v_readlane_b32 s64, v66, 7
	s_nop 3
	v_mov_b32_e32 v194, s64
	s_and_b64 exec, exec, s[54:55]
	ds_write_b32 v140, v66 offset:35328

.LBB0_1536:
	s_or_b64 exec, exec, s[8:9]
	s_and_saveexec_b64 s[8:9], s[46:47]
	s_cbranch_execz .LBB0_1545
	v_mov_b32_e32 v192, v66
	v_mov_b32_e32 v193, v64
	v_mov_b32_e32 v64, 0xf149f2ca
	v_mov_b32_e32 v65, 0
	s_and_saveexec_b64 s[64:65], s[40:41]
	v_mov_b32_e32 v64, v192
	v_mov_b32_e32 v65, v193
	s_or_b64 exec, exec, s[64:65]
	s_waitcnt lgkmcnt(0)
	v_add_f32_dpp v66, v64, v65 row_shr:1 row_mask:0xf bank_mask:0xf bound_ctrl:1
	v_max_f32_e32 v67, v64, v64
	v_max_f32_e32 v66, v66, v67
	v_cndmask_b32_e64 v66, v64, v66, s[48:49]
	v_add_f32_dpp v67, v65, v65 row_shr:1 row_mask:0xf bank_mask:0xf bound_ctrl:1
	v_cndmask_b32_e64 v67, v65, v67, s[48:49]
	v_max_f32_e32 v69, v66, v66
	s_nop 0
	v_add_f32_dpp v68, v66, v67 row_shr:2 row_mask:0xf bank_mask:0xf bound_ctrl:1
	v_max_f32_e32 v68, v68, v69
	v_add_f32_dpp v69, v67, v67 row_shr:2 row_mask:0xf bank_mask:0xf bound_ctrl:1
	v_cndmask_b32_e64 v67, v67, v69, s[50:51]
	v_cndmask_b32_e64 v66, v66, v68, s[50:51]
	v_max_f32_e32 v69, v66, v66
	s_nop 0
	v_add_f32_dpp v68, v66, v67 row_shr:4 row_mask:0xf bank_mask:0xf bound_ctrl:1
	v_max_f32_e32 v68, v68, v69
	v_cndmask_b32_e64 v66, v66, v68, s[52:53]
	v_mov_b32_e32 v68, v194
	v_add_f32_dpp v69, v67, v67 row_shr:4 row_mask:0xf bank_mask:0xf bound_ctrl:1
	v_cndmask_b32_e64 v67, v67, v69, s[52:53]
	v_max_f32_e32 v66, v66, v66
	s_waitcnt lgkmcnt(0)
	v_add_f32_e32 v67, v68, v67
	v_max_f32_e32 v66, v67, v66
	v_mov_b32_e32 v67, 0
	v_sub_f32_e32 v64, v64, v66
	v_mul_f32_e32 v64, 0x3fb8aa3b, v64
	v_mov_b32_dpp v67, v66 row_shr:1 row_mask:0xf bank_mask:0xf
	v_cndmask_b32_e64 v67, v67, v68, s[38:39]
	v_add_f32_e32 v65, v65, v67
	v_sub_f32_e32 v65, v65, v66
	v_mul_f32_e32 v65, 0x3fb8aa3b, v65
	v_exp_f32_e32 v65, v65
	v_exp_f32_e32 v64, v64
	v_add_u32_e32 v67, 0x8800, v144
	ds_write2_b32 v67, v65, v64 offset0:160 offset1:176
	ds_write_b32 v144, v66 offset:35264
	v_readlane_b32 s64, v66, 7
	s_nop 3
	v_mov_b32_e32 v194, s64
	s_and_b64 exec, exec, s[54:55]
	ds_write_b32 v140, v66 offset:35328
